# GEMM K-loop static priorities 3 (blockIdx bit 8) / 1 (others), 0 outside the K-loop, so K-loop waves outrank epilogue waves
# baseline (speedup 1.0000x reference)
.LBB0_286:
	s_and_b32 s0, s33, 7
	s_lshl_b32 s0, s0, 3
	s_lshr_b32 s1, s3, 3
	s_or_b32 s0, s0, s1
	s_lshl_b32 s34, s0, 7
	v_or_b32_e32 v0, s34, v149
	v_lshl_or_b32 v128, v0, 11, v158
	v_lshl_add_u64 v[98:99], s[14:15], 0, v[128:129]
	v_add_co_u32_e32 v6, vcc, 0x10000, v98
	s_lshl_b32 s1, s33, 4
	s_nop 0
	v_addc_co_u32_e32 v7, vcc, 0, v99, vcc
	s_and_b32 s0, s1, 0x7fffff80
	v_add_co_u32_e32 v8, vcc, 0x20000, v98
	v_or_b32_e32 v0, s0, v149
	s_nop 0
	v_addc_co_u32_e32 v9, vcc, 0, v99, vcc
	v_lshl_or_b32 v96, v0, 11, v158
	v_add_co_u32_e32 v10, vcc, 0x30000, v98
	v_mov_b32_e32 v97, v129
	s_nop 0
	v_addc_co_u32_e32 v11, vcc, 0, v99, vcc
	v_lshl_add_u64 v[100:101], s[12:13], 0, v[96:97]
	v_add_co_u32_e32 v12, vcc, s4, v100
	v_addc_co_u32_e32 v13, vcc, 0, v101, vcc
	v_add_co_u32_e32 v46, vcc, s5, v100
	v_addc_co_u32_e32 v47, vcc, 0, v101, vcc
	v_add_co_u32_e32 v48, vcc, s26, v100
	v_addc_co_u32_e32 v49, vcc, 0, v101, vcc
	s_movk_i32 s1, 0x100
	s_mov_b32 s6, s23
	v_mov_b32_e32 v0, 0
	v_mov_b32_e32 v1, v129
	v_mov_b32_e32 v2, v129
	v_mov_b32_e32 v3, v129
	v_mov_b32_e32 v4, 0
	v_mov_b32_e32 v5, v129
	v_mov_b32_e32 v6, v129
	v_mov_b32_e32 v7, v129
	v_mov_b32_e32 v8, 0
	v_mov_b32_e32 v9, v129
	v_mov_b32_e32 v10, v129
	v_mov_b32_e32 v11, v129
	v_mov_b32_e32 v12, 0
	v_mov_b32_e32 v13, v129
	v_lshl_add_u64 v[102:103], v[100:101], 0, s[10:11]
	v_lshl_add_u64 v[104:105], v[100:101], 0, s[18:19]
	v_lshl_add_u64 v[106:107], v[100:101], 0, s[20:21]
	v_lshl_add_u64 v[108:109], v[98:99], 0, s[10:11]
	v_lshl_add_u64 v[110:111], v[98:99], 0, s[18:19]
	v_lshl_add_u64 v[112:113], v[98:99], 0, s[20:21]
	s_barrier
	v_mov_b32_e32 v46, v129
	v_mov_b32_e32 v47, v129
	v_mov_b32_e32 v48, 0
	v_mov_b32_e32 v49, v129
	v_mov_b32_e32 v50, v129
	v_mov_b32_e32 v51, v129
	v_mov_b32_e32 v52, 0
	v_mov_b32_e32 v53, v129
	v_mov_b32_e32 v54, v129
	v_mov_b32_e32 v55, v129
	v_mov_b32_e32 v56, 0
	v_mov_b32_e32 v57, v129
	v_mov_b32_e32 v58, v129
	v_mov_b32_e32 v59, v129
	v_mov_b32_e32 v60, 0
	v_mov_b32_e32 v61, v129
	v_mov_b32_e32 v62, v129
	v_mov_b32_e32 v63, v129
	v_mov_b32_e32 v14, v129
	v_mov_b32_e32 v15, v129
	v_mov_b32_e32 v16, 0
	v_mov_b32_e32 v17, v129
	v_mov_b32_e32 v18, v129
	v_mov_b32_e32 v19, v129
	v_mov_b32_e32 v20, 0
	v_mov_b32_e32 v21, v129
	v_mov_b32_e32 v22, v129
	v_mov_b32_e32 v23, v129
	v_mov_b32_e32 v24, 0
	v_mov_b32_e32 v25, v129
	v_mov_b32_e32 v26, v129
	v_mov_b32_e32 v27, v129
	v_mov_b32_e32 v28, 0
	v_mov_b32_e32 v29, v129
	v_mov_b32_e32 v30, v129
	v_mov_b32_e32 v31, v129
	v_mov_b32_e32 v32, 0
	v_mov_b32_e32 v33, v129
	v_mov_b32_e32 v34, v129
	v_mov_b32_e32 v35, v129
	v_mov_b32_e32 v36, 0
	v_mov_b32_e32 v37, v129
	v_mov_b32_e32 v38, v129
	v_mov_b32_e32 v39, v129
	v_mov_b32_e32 v40, 0
	v_mov_b32_e32 v41, v129
	v_mov_b32_e32 v42, v129
	v_mov_b32_e32 v43, v129
	v_mov_b32_e32 v44, 0
	v_mov_b32_e32 v45, v129
	v_readlane_b32 s100, v253, 0
	v_readlane_b32 s101, v253, 1
	s_load_dwordx2 s[100:101], s[100:101], 0x160
	v_lshrrev_b32_e32 v71, 6, v146
	s_nop 0
	v_readfirstlane_b32 s24, v71
	v_lshrrev_b32_e32 v69, 3, v146
	v_and_b32_e32 v70, 7, v146
	v_xor_b32_e32 v70, v69, v70
	v_and_b32_e32 v70, 7, v70
	v_lshlrev_b32_e32 v70, 4, v70
	v_lshl_or_b32 v68, v69, 11, v70
	v_add_u32_e32 v69, 0x10000, v68
	v_add_u32_e32 v70, 0x20000, v68
	v_add_u32_e32 v71, 0x30000, v68
	s_and_b32 s98, s33, 7
	s_lshl_b32 s98, s98, 3
	s_and_b32 s99, s69, 7
	s_or_b32 s98, s98, s99
	s_lshl_b32 s98, s98, 18
	s_add_u32 s98, s98, 0x2000000
	s_lshr_b32 s99, s33, 3
	s_lshl_b32 s99, s99, 18
	s_add_u32 s99, s99, 0x7200000
	s_lshl_b32 s24, s24, 10
	s_waitcnt lgkmcnt(0)
	s_mov_b32 m0, s99
	s_add_u32 s98, s100, s98
	s_addc_u32 s99, s101, 0
	s_add_u32 s100, s100, m0
	s_addc_u32 s101, s101, 0
	s_add_u32 m0, s24, 0x0
	s_nop 0
	global_load_lds_dwordx4 v68, s[98:99]
	s_add_u32 m0, s24, 0x1000
	s_nop 0
	global_load_lds_dwordx4 v69, s[98:99]
	s_add_u32 m0, s24, 0x2000
	s_nop 0
	global_load_lds_dwordx4 v70, s[98:99]
	s_add_u32 m0, s24, 0x3000
	s_nop 0
	global_load_lds_dwordx4 v71, s[98:99]
	s_add_u32 m0, s24, 0x8000
	s_nop 0
	global_load_lds_dwordx4 v68, s[100:101]
	s_add_u32 m0, s24, 0x9000
	s_nop 0
	global_load_lds_dwordx4 v69, s[100:101]
	s_add_u32 m0, s24, 0xa000
	s_nop 0
	global_load_lds_dwordx4 v70, s[100:101]
	s_add_u32 m0, s24, 0xb000
	s_nop 0
	global_load_lds_dwordx4 v71, s[100:101]
	s_add_u32 s98, s98, 0x80
	s_addc_u32 s99, s99, 0
	s_add_u32 s100, s100, 0x80
	s_addc_u32 s101, s101, 0
	s_waitcnt vmcnt(0)
	s_waitcnt lgkmcnt(0)
	s_barrier
	s_bitcmp1_b32 s69, 8
	s_cbranch_scc1 .Lprio_h287
	s_setprio 1
	s_branch .Lprio_j287
.Lprio_h287:
	s_setprio 3

.LBB0_462:
	s_and_b32 s0, s49, 7
	s_or_b32 s0, s0, s3
	s_lshl_b32 s1, s0, 7
	v_or_b32_e32 v0, s1, v149
	v_lshl_or_b32 v96, v0, 11, v116
	v_lshl_add_u64 v[100:101], s[16:17], 0, v[96:97]
	v_add_co_u32_e32 v12, vcc, 0x10000, v100
	s_lshl_b32 s2, s49, 4
	s_nop 0
	v_addc_co_u32_e32 v13, vcc, 0, v101, vcc
	s_and_b32 s0, s2, 0x7fffff80
	v_add_co_u32_e32 v26, vcc, 0x20000, v100
	v_or_b32_e32 v0, s0, v149
	s_nop 0
	v_addc_co_u32_e32 v27, vcc, 0, v101, vcc
	v_lshl_or_b32 v98, v0, 11, v116
	v_add_co_u32_e32 v28, vcc, 0x30000, v100
	v_mov_b32_e32 v99, v97
	s_nop 0
	v_addc_co_u32_e32 v29, vcc, 0, v101, vcc
	v_lshl_add_u64 v[102:103], s[14:15], 0, v[98:99]
	v_add_co_u32_e32 v30, vcc, s33, v102
	s_waitcnt lgkmcnt(0)
	v_addc_co_u32_e32 v31, vcc, 0, v103, vcc
	v_add_co_u32_e32 v42, vcc, s46, v102
	s_nop 0
	v_addc_co_u32_e32 v43, vcc, 0, v103, vcc
	v_add_co_u32_e32 v44, vcc, s47, v102
	s_nop 0
	v_addc_co_u32_e32 v45, vcc, 0, v103, vcc
	s_movk_i32 s2, 0x100
	s_mov_b32 s43, s27
	v_mov_b32_e32 v60, 0
	v_mov_b32_e32 v61, v97
	v_mov_b32_e32 v62, v97
	v_mov_b32_e32 v63, v97
	v_mov_b32_e32 v40, 0
	v_mov_b32_e32 v41, v97
	v_mov_b32_e32 v42, v97
	v_mov_b32_e32 v43, v97
	v_mov_b32_e32 v28, 0
	v_mov_b32_e32 v29, v97
	v_mov_b32_e32 v30, v97
	v_mov_b32_e32 v31, v97
	v_mov_b32_e32 v12, 0
	v_mov_b32_e32 v13, v97
	v_lshl_add_u64 v[104:105], v[102:103], 0, s[30:31]
	v_lshl_add_u64 v[106:107], v[102:103], 0, s[34:35]
	v_lshl_add_u64 v[108:109], v[102:103], 0, s[36:37]
	v_lshl_add_u64 v[110:111], v[100:101], 0, s[30:31]
	v_lshl_add_u64 v[112:113], v[100:101], 0, s[34:35]
	v_lshl_add_u64 v[114:115], v[100:101], 0, s[36:37]
	s_waitcnt lgkmcnt(0)
	s_barrier
	v_mov_b32_e32 v56, 0
	v_mov_b32_e32 v57, v97
	v_mov_b32_e32 v58, v97
	v_mov_b32_e32 v59, v97
	v_mov_b32_e32 v44, 0
	v_mov_b32_e32 v45, v97
	v_mov_b32_e32 v46, v97
	v_mov_b32_e32 v47, v97
	v_mov_b32_e32 v26, v97
	v_mov_b32_e32 v27, v97
	v_mov_b32_e32 v52, 0
	v_mov_b32_e32 v53, v97
	v_mov_b32_e32 v54, v97
	v_mov_b32_e32 v55, v97
	v_mov_b32_e32 v48, 0
	v_mov_b32_e32 v49, v97
	v_mov_b32_e32 v50, v97
	v_mov_b32_e32 v51, v97
	v_mov_b32_e32 v14, v97
	v_mov_b32_e32 v15, v97
	v_mov_b32_e32 v24, 0
	v_mov_b32_e32 v25, v97
	v_mov_b32_e32 v8, 0
	v_mov_b32_e32 v9, v97
	v_mov_b32_e32 v10, v97
	v_mov_b32_e32 v11, v97
	v_mov_b32_e32 v36, 0
	v_mov_b32_e32 v37, v97
	v_mov_b32_e32 v38, v97
	v_mov_b32_e32 v39, v97
	v_mov_b32_e32 v20, 0
	v_mov_b32_e32 v21, v97
	v_mov_b32_e32 v22, v97
	v_mov_b32_e32 v23, v97
	v_mov_b32_e32 v4, 0
	v_mov_b32_e32 v5, v97
	v_mov_b32_e32 v6, v97
	v_mov_b32_e32 v7, v97
	v_mov_b32_e32 v32, 0
	v_mov_b32_e32 v33, v97
	v_mov_b32_e32 v34, v97
	v_mov_b32_e32 v35, v97
	v_mov_b32_e32 v16, 0
	v_mov_b32_e32 v17, v97
	v_mov_b32_e32 v18, v97
	v_mov_b32_e32 v19, v97
	v_mov_b32_e32 v0, 0
	v_mov_b32_e32 v1, v97
	v_mov_b32_e32 v2, v97
	v_mov_b32_e32 v3, v97
	v_readlane_b32 s100, v253, 0
	v_readlane_b32 s101, v253, 1
	s_load_dwordx2 s[100:101], s[100:101], 0x160
	v_lshrrev_b32_e32 v71, 6, v146
	s_nop 0
	v_readfirstlane_b32 s44, v71
	v_lshrrev_b32_e32 v69, 3, v146
	v_and_b32_e32 v70, 7, v146
	v_xor_b32_e32 v70, v69, v70
	v_and_b32_e32 v70, 7, v70
	v_lshlrev_b32_e32 v70, 4, v70
	v_lshl_or_b32 v68, v69, 11, v70
	v_add_u32_e32 v69, 0x10000, v68
	v_add_u32_e32 v70, 0x20000, v68
	v_add_u32_e32 v71, 0x30000, v68
	s_and_b32 s98, s49, 7
	s_and_b32 s99, s69, 7
	s_lshl_b32 s99, s99, 3
	s_or_b32 s98, s98, s99
	s_lshl_b32 s98, s98, 18
	s_add_u32 s98, s98, 0x2000000
	s_lshr_b32 s99, s49, 3
	s_lshl_b32 s99, s99, 18
	s_add_u32 s99, s99, 0x8c40000
	s_lshl_b32 s44, s44, 10
	s_waitcnt lgkmcnt(0)
	s_mov_b32 m0, s99
	s_add_u32 s98, s100, s98
	s_addc_u32 s99, s101, 0
	s_add_u32 s100, s100, m0
	s_addc_u32 s101, s101, 0
	s_add_u32 m0, s44, 0x0
	s_nop 0
	global_load_lds_dwordx4 v68, s[98:99]
	s_add_u32 m0, s44, 0x1000
	s_nop 0
	global_load_lds_dwordx4 v69, s[98:99]
	s_add_u32 m0, s44, 0x2000
	s_nop 0
	global_load_lds_dwordx4 v70, s[98:99]
	s_add_u32 m0, s44, 0x3000
	s_nop 0
	global_load_lds_dwordx4 v71, s[98:99]
	s_add_u32 m0, s44, 0x8000
	s_nop 0
	global_load_lds_dwordx4 v68, s[100:101]
	s_add_u32 m0, s44, 0x9000
	s_nop 0
	global_load_lds_dwordx4 v69, s[100:101]
	s_add_u32 m0, s44, 0xa000
	s_nop 0
	global_load_lds_dwordx4 v70, s[100:101]
	s_add_u32 m0, s44, 0xb000
	s_nop 0
	global_load_lds_dwordx4 v71, s[100:101]
	s_add_u32 s98, s98, 0x80
	s_addc_u32 s99, s99, 0
	s_add_u32 s100, s100, 0x80
	s_addc_u32 s101, s101, 0
	s_waitcnt vmcnt(0)
	s_waitcnt lgkmcnt(0)
	s_barrier
	s_bitcmp1_b32 s69, 8
	s_cbranch_scc1 .Lprio_h463
	s_setprio 1
	s_branch .Lprio_j463

.LBB0_527:
	s_and_b32 s0, s43, 7
	s_lshl_b32 s0, s0, 3
	s_lshr_b32 s1, s3, 3
	s_or_b32 s0, s0, s1
	s_lshl_b32 s44, s0, 7
	v_or_b32_e32 v0, s44, v149
	v_lshl_or_b32 v160, v0, 11, v159
	v_lshl_add_u64 v[30:31], s[22:23], 0, v[160:161]
	v_add_co_u32_e32 v4, vcc, 0x10000, v30
	s_lshl_b32 s1, s43, 4
	s_nop 0
	v_addc_co_u32_e32 v5, vcc, 0, v31, vcc
	s_and_b32 s0, s1, 0x7fffff80
	v_add_co_u32_e32 v12, vcc, 0x20000, v30
	v_or_b32_e32 v0, s0, v149
	s_nop 0
	v_addc_co_u32_e32 v13, vcc, 0, v31, vcc
	v_lshl_or_b32 v24, v0, 11, v159
	v_add_co_u32_e32 v16, vcc, 0x30000, v30
	v_mov_b32_e32 v25, v161
	s_nop 0
	v_addc_co_u32_e32 v17, vcc, 0, v31, vcc
	v_lshl_add_u64 v[52:53], s[16:17], 0, v[24:25]
	v_add_co_u32_e32 v18, vcc, s38, v52
	s_nop 0
	v_addc_co_u32_e32 v19, vcc, 0, v53, vcc
	v_add_co_u32_e32 v28, vcc, s39, v52
	s_nop 0
	v_addc_co_u32_e32 v29, vcc, 0, v53, vcc
	v_add_co_u32_e32 v58, vcc, s40, v52
	s_nop 0
	v_addc_co_u32_e32 v59, vcc, 0, v53, vcc
	s_nop 0
	s_nop 0
	s_nop 0
	s_movk_i32 s1, 0x100
	s_mov_b32 s6, s37
	v_mov_b32_e32 v8, 0
	v_mov_b32_e32 v9, v161
	v_mov_b32_e32 v10, v161
	v_mov_b32_e32 v11, v161
	v_mov_b32_e32 v26, 0
	v_mov_b32_e32 v27, v161
	v_mov_b32_e32 v28, v161
	v_mov_b32_e32 v29, v161
	v_mov_b32_e32 v16, 0
	v_mov_b32_e32 v17, v161
	v_mov_b32_e32 v18, v161
	v_mov_b32_e32 v19, v161
	v_mov_b32_e32 v60, 0
	v_mov_b32_e32 v61, v161
	v_lshl_add_u64 v[58:59], v[52:53], 0, s[14:15]
	v_lshl_add_u64 v[104:105], v[52:53], 0, s[30:31]
	v_lshl_add_u64 v[106:107], v[52:53], 0, s[34:35]
	v_lshl_add_u64 v[108:109], v[30:31], 0, s[14:15]
	v_lshl_add_u64 v[110:111], v[30:31], 0, s[30:31]
	v_lshl_add_u64 v[112:113], v[30:31], 0, s[34:35]
	s_barrier
	v_mov_b32_e32 v88, 0
	v_mov_b32_e32 v89, v161
	v_mov_b32_e32 v90, v161
	v_mov_b32_e32 v91, v161
	v_mov_b32_e32 v76, 0
	v_mov_b32_e32 v77, v161
	v_mov_b32_e32 v78, v161
	v_mov_b32_e32 v79, v161
	v_mov_b32_e32 v80, 0
	v_mov_b32_e32 v81, v161
	v_mov_b32_e32 v82, v161
	v_mov_b32_e32 v83, v161
	v_mov_b32_e32 v84, 0
	v_mov_b32_e32 v85, v161
	v_mov_b32_e32 v86, v161
	v_mov_b32_e32 v87, v161
	v_mov_b32_e32 v74, v161
	v_mov_b32_e32 v75, v161
	v_mov_b32_e32 v62, v161
	v_mov_b32_e32 v63, v161
	v_mov_b32_e32 v36, 0
	v_mov_b32_e32 v37, v161
	v_mov_b32_e32 v38, v161
	v_mov_b32_e32 v39, v161
	v_mov_b32_e32 v54, 0
	v_mov_b32_e32 v55, v161
	v_mov_b32_e32 v56, v161
	v_mov_b32_e32 v57, v161
	v_mov_b32_e32 v32, 0
	v_mov_b32_e32 v33, v161
	v_mov_b32_e32 v34, v161
	v_mov_b32_e32 v35, v161
	v_mov_b32_e32 v64, 0
	v_mov_b32_e32 v65, v161
	v_mov_b32_e32 v66, v161
	v_mov_b32_e32 v67, v161
	v_mov_b32_e32 v40, 0
	v_mov_b32_e32 v41, v161
	v_mov_b32_e32 v42, v161
	v_mov_b32_e32 v43, v161
	v_mov_b32_e32 v48, 0
	v_mov_b32_e32 v49, v161
	v_mov_b32_e32 v50, v161
	v_mov_b32_e32 v51, v161
	v_mov_b32_e32 v68, 0
	v_mov_b32_e32 v69, v161
	v_mov_b32_e32 v70, v161
	v_mov_b32_e32 v71, v161
	v_mov_b32_e32 v72, 0
	v_mov_b32_e32 v73, v161
	v_readlane_b32 s100, v253, 0
	v_readlane_b32 s101, v253, 1
	s_load_dwordx2 s[100:101], s[100:101], 0x160
	v_lshrrev_b32_e32 v7, 6, v146
	s_nop 0
	v_readfirstlane_b32 s8, v7
	v_lshrrev_b32_e32 v5, 3, v146
	v_and_b32_e32 v6, 7, v146
	v_xor_b32_e32 v6, v5, v6
	v_and_b32_e32 v6, 7, v6
	v_lshlrev_b32_e32 v6, 4, v6
	v_lshl_or_b32 v4, v5, 11, v6
	v_add_u32_e32 v5, 0x10000, v4
	v_add_u32_e32 v6, 0x20000, v4
	v_add_u32_e32 v7, 0x30000, v4
	s_and_b32 s98, s43, 7
	s_lshl_b32 s98, s98, 3
	s_and_b32 s99, s69, 7
	s_or_b32 s98, s98, s99
	s_lshl_b32 s98, s98, 18
	s_add_u32 s98, s98, 0xdc40000
	s_lshr_b32 s99, s43, 3
	s_lshl_b32 s99, s99, 18
	s_add_u32 s99, s99, 0x7700000
	s_lshl_b32 s8, s8, 10
	s_waitcnt lgkmcnt(0)
	s_mov_b32 m0, s99
	s_add_u32 s98, s100, s98
	s_addc_u32 s99, s101, 0
	s_add_u32 s100, s100, m0
	s_addc_u32 s101, s101, 0
	s_add_u32 m0, s8, 0x0
	s_nop 0
	global_load_lds_dwordx4 v4, s[98:99]
	s_add_u32 m0, s8, 0x1000
	s_nop 0
	global_load_lds_dwordx4 v5, s[98:99]
	s_add_u32 m0, s8, 0x2000
	s_nop 0
	global_load_lds_dwordx4 v6, s[98:99]
	s_add_u32 m0, s8, 0x3000
	s_nop 0
	global_load_lds_dwordx4 v7, s[98:99]
	s_add_u32 m0, s8, 0x8000
	s_nop 0
	global_load_lds_dwordx4 v4, s[100:101]
	s_add_u32 m0, s8, 0x9000
	s_nop 0
	global_load_lds_dwordx4 v5, s[100:101]
	s_add_u32 m0, s8, 0xa000
	s_nop 0
	global_load_lds_dwordx4 v6, s[100:101]
	s_add_u32 m0, s8, 0xb000
	s_nop 0
	global_load_lds_dwordx4 v7, s[100:101]
	s_add_u32 s98, s98, 0x80
	s_addc_u32 s99, s99, 0
	s_add_u32 s100, s100, 0x80
	s_addc_u32 s101, s101, 0
	s_waitcnt vmcnt(0)
	s_waitcnt lgkmcnt(0)
	s_barrier
	s_bitcmp1_b32 s69, 8
	s_cbranch_scc1 .Lprio_h528
	s_setprio 1
	s_branch .Lprio_j528

.LBB0_675:
	s_and_b32 s0, s9, 7
	s_or_b32 s0, s0, s3
	s_lshl_b32 s1, s0, 7
	v_or_b32_e32 v0, s1, v149
	v_lshl_or_b32 v96, v0, 11, v116
	s_waitcnt vmcnt(1)
	v_lshl_add_u64 v[100:101], s[18:19], 0, v[96:97]
	v_add_co_u32_e32 v12, vcc, 0x10000, v100
	s_lshl_b32 s2, s9, 4
	s_nop 0
	v_addc_co_u32_e32 v13, vcc, 0, v101, vcc
	s_and_b32 s0, s2, 0x7fffff80
	v_add_co_u32_e32 v26, vcc, 0x20000, v100
	v_or_b32_e32 v0, s0, v149
	s_nop 0
	v_addc_co_u32_e32 v27, vcc, 0, v101, vcc
	v_lshl_or_b32 v98, v0, 11, v116
	v_add_co_u32_e32 v28, vcc, 0x30000, v100
	v_mov_b32_e32 v99, v97
	s_nop 0
	v_addc_co_u32_e32 v29, vcc, 0, v101, vcc
	v_lshl_add_u64 v[102:103], s[16:17], 0, v[98:99]
	v_add_co_u32_e32 v30, vcc, s6, v102
	s_waitcnt lgkmcnt(0)
	v_addc_co_u32_e32 v31, vcc, 0, v103, vcc
	v_add_co_u32_e32 v42, vcc, s7, v102
	s_nop 0
	v_addc_co_u32_e32 v43, vcc, 0, v103, vcc
	v_add_co_u32_e32 v44, vcc, s8, v102
	s_nop 0
	v_addc_co_u32_e32 v45, vcc, 0, v103, vcc
	s_movk_i32 s2, 0x100
	s_mov_b32 s42, s29
	v_mov_b32_e32 v64, 0
	v_mov_b32_e32 v65, v97
	v_mov_b32_e32 v66, v97
	v_mov_b32_e32 v67, v97
	v_mov_b32_e32 v40, 0
	v_mov_b32_e32 v41, v97
	v_mov_b32_e32 v42, v97
	v_mov_b32_e32 v43, v97
	v_mov_b32_e32 v28, 0
	v_mov_b32_e32 v29, v97
	v_mov_b32_e32 v30, v97
	v_mov_b32_e32 v31, v97
	v_mov_b32_e32 v12, 0
	v_mov_b32_e32 v13, v97
	v_lshl_add_u64 v[104:105], v[102:103], 0, s[30:31]
	v_lshl_add_u64 v[106:107], v[102:103], 0, s[34:35]
	v_lshl_add_u64 v[108:109], v[102:103], 0, s[36:37]
	v_lshl_add_u64 v[110:111], v[100:101], 0, s[30:31]
	v_lshl_add_u64 v[112:113], v[100:101], 0, s[34:35]
	v_lshl_add_u64 v[114:115], v[100:101], 0, s[36:37]
	s_waitcnt lgkmcnt(0)
	s_barrier
	v_mov_b32_e32 v60, 0
	v_mov_b32_e32 v61, v97
	v_mov_b32_e32 v62, v97
	v_mov_b32_e32 v63, v97
	v_mov_b32_e32 v44, 0
	v_mov_b32_e32 v45, v97
	v_mov_b32_e32 v46, v97
	v_mov_b32_e32 v47, v97
	v_mov_b32_e32 v26, v97
	v_mov_b32_e32 v27, v97
	v_mov_b32_e32 v52, 0
	v_mov_b32_e32 v53, v97
	v_mov_b32_e32 v54, v97
	v_mov_b32_e32 v55, v97
	v_mov_b32_e32 v48, 0
	v_mov_b32_e32 v49, v97
	v_mov_b32_e32 v50, v97
	v_mov_b32_e32 v51, v97
	v_mov_b32_e32 v14, v97
	v_mov_b32_e32 v15, v97
	v_mov_b32_e32 v24, 0
	v_mov_b32_e32 v25, v97
	v_mov_b32_e32 v8, 0
	v_mov_b32_e32 v9, v97
	v_mov_b32_e32 v10, v97
	v_mov_b32_e32 v11, v97
	v_mov_b32_e32 v36, 0
	v_mov_b32_e32 v37, v97
	v_mov_b32_e32 v38, v97
	v_mov_b32_e32 v39, v97
	v_mov_b32_e32 v20, 0
	v_mov_b32_e32 v21, v97
	v_mov_b32_e32 v22, v97
	v_mov_b32_e32 v23, v97
	v_mov_b32_e32 v4, 0
	v_mov_b32_e32 v5, v97
	v_mov_b32_e32 v6, v97
	v_mov_b32_e32 v7, v97
	v_mov_b32_e32 v32, 0
	v_mov_b32_e32 v33, v97
	v_mov_b32_e32 v34, v97
	v_mov_b32_e32 v35, v97
	v_mov_b32_e32 v16, 0
	v_mov_b32_e32 v17, v97
	v_mov_b32_e32 v18, v97
	v_mov_b32_e32 v19, v97
	v_mov_b32_e32 v0, 0
	v_mov_b32_e32 v1, v97
	v_mov_b32_e32 v2, v97
	v_mov_b32_e32 v3, v97
	v_readlane_b32 s100, v253, 0
	v_readlane_b32 s101, v253, 1
	s_load_dwordx2 s[100:101], s[100:101], 0x160
	v_lshrrev_b32_e32 v71, 6, v146
	s_nop 0
	v_readfirstlane_b32 s44, v71
	v_lshrrev_b32_e32 v69, 3, v146
	v_and_b32_e32 v70, 7, v146
	v_xor_b32_e32 v70, v69, v70
	v_and_b32_e32 v70, 7, v70
	v_lshlrev_b32_e32 v70, 4, v70
	v_lshl_or_b32 v68, v69, 11, v70
	v_add_u32_e32 v69, 0x10000, v68
	v_add_u32_e32 v70, 0x20000, v68
	v_add_u32_e32 v71, 0x30000, v68
	s_and_b32 s98, s9, 7
	s_and_b32 s99, s69, 7
	s_lshl_b32 s99, s99, 3
	s_or_b32 s98, s98, s99
	s_lshl_b32 s98, s98, 18
	s_add_u32 s98, s98, 0x2000000
	s_lshr_b32 s99, s9, 3
	s_lshl_b32 s99, s99, 18
	s_add_u32 s99, s99, 0x8e40000
	s_lshl_b32 s44, s44, 10
	s_waitcnt lgkmcnt(0)
	s_mov_b32 m0, s99
	s_add_u32 s98, s100, s98
	s_addc_u32 s99, s101, 0
	s_add_u32 s100, s100, m0
	s_addc_u32 s101, s101, 0
	s_add_u32 m0, s44, 0x0
	s_nop 0
	global_load_lds_dwordx4 v68, s[98:99]
	s_add_u32 m0, s44, 0x1000
	s_nop 0
	global_load_lds_dwordx4 v69, s[98:99]
	s_add_u32 m0, s44, 0x2000
	s_nop 0
	global_load_lds_dwordx4 v70, s[98:99]
	s_add_u32 m0, s44, 0x3000
	s_nop 0
	global_load_lds_dwordx4 v71, s[98:99]
	s_add_u32 m0, s44, 0x8000
	s_nop 0
	global_load_lds_dwordx4 v68, s[100:101]
	s_add_u32 m0, s44, 0x9000
	s_nop 0
	global_load_lds_dwordx4 v69, s[100:101]
	s_add_u32 m0, s44, 0xa000
	s_nop 0
	global_load_lds_dwordx4 v70, s[100:101]
	s_add_u32 m0, s44, 0xb000
	s_nop 0
	global_load_lds_dwordx4 v71, s[100:101]
	s_add_u32 s98, s98, 0x80
	s_addc_u32 s99, s99, 0
	s_add_u32 s100, s100, 0x80
	s_addc_u32 s101, s101, 0
	s_waitcnt vmcnt(0)
	s_waitcnt lgkmcnt(0)
	s_barrier
	s_bitcmp1_b32 s69, 8
	s_cbranch_scc1 .Lprio_h676
	s_setprio 1
	s_branch .Lprio_j676

.LBB0_739:
	s_and_b32 s8, s7, 7
	s_or_b32 s8, s8, s0
	s_lshl_b32 s8, s8, 7
	v_or_b32_e32 v0, s8, v149
	v_lshl_or_b32 v96, v0, 11, v116
	s_waitcnt vmcnt(1)
	v_lshl_add_u64 v[100:101], s[18:19], 0, v[96:97]
	v_add_co_u32_e32 v2, vcc, 0x10000, v100
	s_lshl_b32 s9, s7, 4
	s_nop 0
	v_addc_co_u32_e32 v3, vcc, 0, v101, vcc
	s_and_b32 s9, s9, 0x7fffff80
	v_add_co_u32_e32 v4, vcc, 0x20000, v100
	v_or_b32_e32 v0, s9, v149
	s_nop 0
	v_addc_co_u32_e32 v5, vcc, 0, v101, vcc
	v_lshl_or_b32 v98, v0, 11, v116
	v_add_co_u32_e32 v6, vcc, 0x30000, v100
	v_mov_b32_e32 v99, v97
	s_nop 0
	v_addc_co_u32_e32 v7, vcc, 0, v101, vcc
	v_lshl_add_u64 v[102:103], s[16:17], 0, v[98:99]
	v_add_co_u32_e32 v12, vcc, s3, v102
	s_nop 0
	v_addc_co_u32_e32 v13, vcc, 0, v103, vcc
	v_add_co_u32_e32 v14, vcc, s4, v102
	s_nop 0
	v_addc_co_u32_e32 v15, vcc, 0, v103, vcc
	v_add_co_u32_e32 v48, vcc, s5, v102
	s_nop 0
	v_addc_co_u32_e32 v49, vcc, 0, v103, vcc
	s_movk_i32 s10, 0x100
	s_mov_b32 s12, s35
	v_mov_b32_e32 v8, 0
	v_mov_b32_e32 v9, v97
	v_mov_b32_e32 v10, v97
	v_mov_b32_e32 v11, v97
	v_mov_b32_e32 v0, 0
	v_mov_b32_e32 v1, v97
	v_mov_b32_e32 v2, v97
	v_mov_b32_e32 v3, v97
	v_mov_b32_e32 v12, 0
	v_mov_b32_e32 v13, v97
	v_mov_b32_e32 v14, v97
	v_mov_b32_e32 v15, v97
	v_mov_b32_e32 v4, 0
	v_mov_b32_e32 v5, v97
	v_lshl_add_u64 v[104:105], v[102:103], 0, s[26:27]
	v_lshl_add_u64 v[106:107], v[102:103], 0, s[28:29]
	v_lshl_add_u64 v[108:109], v[102:103], 0, s[30:31]
	v_lshl_add_u64 v[110:111], v[100:101], 0, s[26:27]
	v_lshl_add_u64 v[112:113], v[100:101], 0, s[28:29]
	v_lshl_add_u64 v[114:115], v[100:101], 0, s[30:31]
	s_barrier
	v_mov_b32_e32 v6, v97
	v_mov_b32_e32 v7, v97
	v_mov_b32_e32 v48, 0
	v_mov_b32_e32 v49, v97
	v_mov_b32_e32 v50, v97
	v_mov_b32_e32 v51, v97
	v_mov_b32_e32 v60, 0
	v_mov_b32_e32 v61, v97
	v_mov_b32_e32 v62, v97
	v_mov_b32_e32 v63, v97
	v_mov_b32_e32 v56, 0
	v_mov_b32_e32 v57, v97
	v_mov_b32_e32 v58, v97
	v_mov_b32_e32 v59, v97
	v_mov_b32_e32 v52, 0
	v_mov_b32_e32 v53, v97
	v_mov_b32_e32 v54, v97
	v_mov_b32_e32 v55, v97
	v_mov_b32_e32 v32, 0
	v_mov_b32_e32 v33, v97
	v_mov_b32_e32 v34, v97
	v_mov_b32_e32 v35, v97
	v_mov_b32_e32 v24, 0
	v_mov_b32_e32 v25, v97
	v_mov_b32_e32 v26, v97
	v_mov_b32_e32 v27, v97
	v_mov_b32_e32 v20, 0
	v_mov_b32_e32 v21, v97
	v_mov_b32_e32 v22, v97
	v_mov_b32_e32 v23, v97
	v_mov_b32_e32 v16, 0
	v_mov_b32_e32 v17, v97
	v_mov_b32_e32 v18, v97
	v_mov_b32_e32 v19, v97
	v_mov_b32_e32 v40, 0
	v_mov_b32_e32 v41, v97
	v_mov_b32_e32 v42, v97
	v_mov_b32_e32 v43, v97
	v_mov_b32_e32 v36, 0
	v_mov_b32_e32 v37, v97
	v_mov_b32_e32 v38, v97
	v_mov_b32_e32 v39, v97
	v_mov_b32_e32 v28, 0
	v_mov_b32_e32 v29, v97
	v_mov_b32_e32 v30, v97
	v_mov_b32_e32 v31, v97
	v_mov_b32_e32 v44, 0
	v_mov_b32_e32 v45, v97
	v_mov_b32_e32 v46, v97
	v_mov_b32_e32 v47, v97
	v_readlane_b32 s100, v253, 0
	v_readlane_b32 s101, v253, 1
	s_load_dwordx2 s[100:101], s[100:101], 0x160
	v_lshrrev_b32_e32 v71, 6, v146
	s_nop 0
	v_readfirstlane_b32 s14, v71
	v_lshrrev_b32_e32 v69, 3, v146
	v_and_b32_e32 v70, 7, v146
	v_xor_b32_e32 v70, v69, v70
	v_and_b32_e32 v70, 7, v70
	v_lshlrev_b32_e32 v70, 4, v70
	v_lshl_or_b32 v68, v69, 11, v70
	v_add_u32_e32 v69, 0x10000, v68
	v_add_u32_e32 v70, 0x20000, v68
	v_add_u32_e32 v71, 0x30000, v68
	s_and_b32 s98, s7, 7
	s_and_b32 s99, s69, 7
	s_lshl_b32 s99, s99, 3
	s_or_b32 s98, s98, s99
	s_lshl_b32 s98, s98, 18
	s_add_u32 s98, s98, 0xdc40000
	s_lshr_b32 s99, s7, 3
	s_lshl_b32 s99, s99, 18
	s_add_u32 s99, s99, 0x7f00000
	s_lshl_b32 s14, s14, 10
	s_waitcnt lgkmcnt(0)
	s_mov_b32 m0, s99
	s_add_u32 s98, s100, s98
	s_addc_u32 s99, s101, 0
	s_add_u32 s100, s100, m0
	s_addc_u32 s101, s101, 0
	s_add_u32 m0, s14, 0x0
	s_nop 0
	global_load_lds_dwordx4 v68, s[98:99]
	s_add_u32 m0, s14, 0x1000
	s_nop 0
	global_load_lds_dwordx4 v69, s[98:99]
	s_add_u32 m0, s14, 0x2000
	s_nop 0
	global_load_lds_dwordx4 v70, s[98:99]
	s_add_u32 m0, s14, 0x3000
	s_nop 0
	global_load_lds_dwordx4 v71, s[98:99]
	s_add_u32 m0, s14, 0x8000
	s_nop 0
	global_load_lds_dwordx4 v68, s[100:101]
	s_add_u32 m0, s14, 0x9000
	s_nop 0
	global_load_lds_dwordx4 v69, s[100:101]
	s_add_u32 m0, s14, 0xa000
	s_nop 0
	global_load_lds_dwordx4 v70, s[100:101]
	s_add_u32 m0, s14, 0xb000
	s_nop 0
	global_load_lds_dwordx4 v71, s[100:101]
	s_add_u32 s98, s98, 0x80
	s_addc_u32 s99, s99, 0
	s_add_u32 s100, s100, 0x80
	s_addc_u32 s101, s101, 0
	s_waitcnt vmcnt(0)
	s_waitcnt lgkmcnt(0)
	s_barrier
	s_bitcmp1_b32 s69, 8
	s_cbranch_scc1 .Lprio_h740
	s_setprio 1
	s_branch .Lprio_j740

.LBB0_1100:
	s_and_b32 s0, s9, 7
	s_or_b32 s0, s0, s3
	s_lshl_b32 s1, s0, 7
	v_or_b32_e32 v0, s1, v149
	v_lshl_or_b32 v96, v0, 11, v116
	s_waitcnt vmcnt(1)
	v_lshl_add_u64 v[100:101], s[18:19], 0, v[96:97]
	v_add_co_u32_e32 v12, vcc, 0x10000, v100
	s_lshl_b32 s2, s9, 4
	s_nop 0
	v_addc_co_u32_e32 v13, vcc, 0, v101, vcc
	s_and_b32 s0, s2, 0x7fffff80
	v_add_co_u32_e32 v26, vcc, 0x20000, v100
	v_or_b32_e32 v0, s0, v149
	s_nop 0
	v_addc_co_u32_e32 v27, vcc, 0, v101, vcc
	v_lshl_or_b32 v98, v0, 11, v116
	v_add_co_u32_e32 v28, vcc, 0x30000, v100
	v_mov_b32_e32 v99, v97
	s_nop 0
	v_addc_co_u32_e32 v29, vcc, 0, v101, vcc
	v_lshl_add_u64 v[102:103], s[16:17], 0, v[98:99]
	v_add_co_u32_e32 v30, vcc, s6, v102
	s_waitcnt lgkmcnt(0)
	v_addc_co_u32_e32 v31, vcc, 0, v103, vcc
	v_add_co_u32_e32 v42, vcc, s7, v102
	s_nop 0
	v_addc_co_u32_e32 v43, vcc, 0, v103, vcc
	v_add_co_u32_e32 v44, vcc, s8, v102
	s_nop 0
	v_addc_co_u32_e32 v45, vcc, 0, v103, vcc
	s_movk_i32 s2, 0x100
	s_mov_b32 s40, s27
	v_mov_b32_e32 v64, 0
	v_mov_b32_e32 v65, v97
	v_mov_b32_e32 v66, v97
	v_mov_b32_e32 v67, v97
	v_mov_b32_e32 v40, 0
	v_mov_b32_e32 v41, v97
	v_mov_b32_e32 v42, v97
	v_mov_b32_e32 v43, v97
	v_mov_b32_e32 v28, 0
	v_mov_b32_e32 v29, v97
	v_mov_b32_e32 v30, v97
	v_mov_b32_e32 v31, v97
	v_mov_b32_e32 v12, 0
	v_mov_b32_e32 v13, v97
	v_lshl_add_u64 v[104:105], v[102:103], 0, s[28:29]
	v_lshl_add_u64 v[106:107], v[102:103], 0, s[30:31]
	v_lshl_add_u64 v[108:109], v[102:103], 0, s[34:35]
	v_lshl_add_u64 v[110:111], v[100:101], 0, s[28:29]
	v_lshl_add_u64 v[112:113], v[100:101], 0, s[30:31]
	v_lshl_add_u64 v[114:115], v[100:101], 0, s[34:35]
	s_waitcnt lgkmcnt(0)
	s_barrier
	v_mov_b32_e32 v60, 0
	v_mov_b32_e32 v61, v97
	v_mov_b32_e32 v62, v97
	v_mov_b32_e32 v63, v97
	v_mov_b32_e32 v44, 0
	v_mov_b32_e32 v45, v97
	v_mov_b32_e32 v46, v97
	v_mov_b32_e32 v47, v97
	v_mov_b32_e32 v26, v97
	v_mov_b32_e32 v27, v97
	v_mov_b32_e32 v52, 0
	v_mov_b32_e32 v53, v97
	v_mov_b32_e32 v54, v97
	v_mov_b32_e32 v55, v97
	v_mov_b32_e32 v48, 0
	v_mov_b32_e32 v49, v97
	v_mov_b32_e32 v50, v97
	v_mov_b32_e32 v51, v97
	v_mov_b32_e32 v14, v97
	v_mov_b32_e32 v15, v97
	v_mov_b32_e32 v24, 0
	v_mov_b32_e32 v25, v97
	v_mov_b32_e32 v8, 0
	v_mov_b32_e32 v9, v97
	v_mov_b32_e32 v10, v97
	v_mov_b32_e32 v11, v97
	v_mov_b32_e32 v36, 0
	v_mov_b32_e32 v37, v97
	v_mov_b32_e32 v38, v97
	v_mov_b32_e32 v39, v97
	v_mov_b32_e32 v20, 0
	v_mov_b32_e32 v21, v97
	v_mov_b32_e32 v22, v97
	v_mov_b32_e32 v23, v97
	v_mov_b32_e32 v4, 0
	v_mov_b32_e32 v5, v97
	v_mov_b32_e32 v6, v97
	v_mov_b32_e32 v7, v97
	v_mov_b32_e32 v32, 0
	v_mov_b32_e32 v33, v97
	v_mov_b32_e32 v34, v97
	v_mov_b32_e32 v35, v97
	v_mov_b32_e32 v16, 0
	v_mov_b32_e32 v17, v97
	v_mov_b32_e32 v18, v97
	v_mov_b32_e32 v19, v97
	v_mov_b32_e32 v0, 0
	v_mov_b32_e32 v1, v97
	v_mov_b32_e32 v2, v97
	v_mov_b32_e32 v3, v97
	v_readlane_b32 s100, v253, 0
	v_readlane_b32 s101, v253, 1
	s_load_dwordx2 s[100:101], s[100:101], 0x160
	v_lshrrev_b32_e32 v71, 6, v146
	s_nop 0
	v_readfirstlane_b32 s42, v71
	v_lshrrev_b32_e32 v69, 3, v146
	v_and_b32_e32 v70, 7, v146
	v_xor_b32_e32 v70, v69, v70
	v_and_b32_e32 v70, 7, v70
	v_lshlrev_b32_e32 v70, 4, v70
	v_lshl_or_b32 v68, v69, 11, v70
	v_add_u32_e32 v69, 0x10000, v68
	v_add_u32_e32 v70, 0x20000, v68
	v_add_u32_e32 v71, 0x30000, v68
	s_and_b32 s98, s9, 7
	s_and_b32 s99, s69, 7
	s_lshl_b32 s99, s99, 3
	s_or_b32 s98, s98, s99
	s_lshl_b32 s98, s98, 18
	s_add_u32 s98, s98, 0x2000000
	s_lshr_b32 s99, s9, 3
	s_lshl_b32 s99, s99, 18
	s_add_u32 s99, s99, 0x9040000
	s_lshl_b32 s42, s42, 10
	s_waitcnt lgkmcnt(0)
	s_mov_b32 m0, s99
	s_add_u32 s98, s100, s98
	s_addc_u32 s99, s101, 0
	s_add_u32 s100, s100, m0
	s_addc_u32 s101, s101, 0
	s_add_u32 m0, s42, 0x0
	s_nop 0
	global_load_lds_dwordx4 v68, s[98:99]
	s_add_u32 m0, s42, 0x1000
	s_nop 0
	global_load_lds_dwordx4 v69, s[98:99]
	s_add_u32 m0, s42, 0x2000
	s_nop 0
	global_load_lds_dwordx4 v70, s[98:99]
	s_add_u32 m0, s42, 0x3000
	s_nop 0
	global_load_lds_dwordx4 v71, s[98:99]
	s_add_u32 m0, s42, 0x8000
	s_nop 0
	global_load_lds_dwordx4 v68, s[100:101]
	s_add_u32 m0, s42, 0x9000
	s_nop 0
	global_load_lds_dwordx4 v69, s[100:101]
	s_add_u32 m0, s42, 0xa000
	s_nop 0
	global_load_lds_dwordx4 v70, s[100:101]
	s_add_u32 m0, s42, 0xb000
	s_nop 0
	global_load_lds_dwordx4 v71, s[100:101]
	s_add_u32 s98, s98, 0x80
	s_addc_u32 s99, s99, 0
	s_add_u32 s100, s100, 0x80
	s_addc_u32 s101, s101, 0
	s_waitcnt vmcnt(0)
	s_waitcnt lgkmcnt(0)
	s_barrier
	s_bitcmp1_b32 s69, 8
	s_cbranch_scc1 .Lprio_h1101
	s_setprio 1
	s_branch .Lprio_j1101

.LBB0_1165:
	s_and_b32 s0, s45, 7
	s_lshl_b32 s0, s0, 3
	s_lshr_b32 s1, s3, 3
	s_or_b32 s0, s0, s1
	s_lshl_b32 s46, s0, 7
	v_or_b32_e32 v0, s46, v149
	v_lshl_or_b32 v130, v0, 11, v129
	v_lshl_add_u64 v[30:31], s[22:23], 0, v[130:131]
	v_add_co_u32_e32 v4, vcc, 0x10000, v30
	s_lshl_b32 s1, s45, 4
	s_nop 0
	v_addc_co_u32_e32 v5, vcc, 0, v31, vcc
	s_and_b32 s0, s1, 0x7fffff80
	v_add_co_u32_e32 v12, vcc, 0x20000, v30
	v_or_b32_e32 v0, s0, v149
	s_nop 0
	v_addc_co_u32_e32 v13, vcc, 0, v31, vcc
	v_lshl_or_b32 v24, v0, 11, v129
	v_add_co_u32_e32 v16, vcc, 0x30000, v30
	v_mov_b32_e32 v25, v131
	s_nop 0
	v_addc_co_u32_e32 v17, vcc, 0, v31, vcc
	v_lshl_add_u64 v[52:53], s[20:21], 0, v[24:25]
	v_add_co_u32_e32 v18, vcc, s8, v52
	s_nop 0
	v_addc_co_u32_e32 v19, vcc, 0, v53, vcc
	v_add_co_u32_e32 v28, vcc, s9, v52
	s_nop 0
	v_addc_co_u32_e32 v29, vcc, 0, v53, vcc
	v_add_co_u32_e32 v58, vcc, s38, v52
	s_nop 0
	v_addc_co_u32_e32 v59, vcc, 0, v53, vcc
	s_nop 0
	s_nop 0
	s_nop 0
	s_movk_i32 s1, 0x100
	s_mov_b32 s6, s37
	v_mov_b32_e32 v8, 0
	v_mov_b32_e32 v9, v131
	v_mov_b32_e32 v10, v131
	v_mov_b32_e32 v11, v131
	v_mov_b32_e32 v26, 0
	v_mov_b32_e32 v27, v131
	v_mov_b32_e32 v28, v131
	v_mov_b32_e32 v29, v131
	v_mov_b32_e32 v16, 0
	v_mov_b32_e32 v17, v131
	v_mov_b32_e32 v18, v131
	v_mov_b32_e32 v19, v131
	v_mov_b32_e32 v60, 0
	v_mov_b32_e32 v61, v131
	v_lshl_add_u64 v[58:59], v[52:53], 0, s[18:19]
	v_lshl_add_u64 v[104:105], v[52:53], 0, s[30:31]
	v_lshl_add_u64 v[106:107], v[52:53], 0, s[34:35]
	v_lshl_add_u64 v[108:109], v[30:31], 0, s[18:19]
	v_lshl_add_u64 v[110:111], v[30:31], 0, s[30:31]
	v_lshl_add_u64 v[112:113], v[30:31], 0, s[34:35]
	s_barrier
	v_mov_b32_e32 v88, 0
	v_mov_b32_e32 v89, v131
	v_mov_b32_e32 v90, v131
	v_mov_b32_e32 v91, v131
	v_mov_b32_e32 v76, 0
	v_mov_b32_e32 v77, v131
	v_mov_b32_e32 v78, v131
	v_mov_b32_e32 v79, v131
	v_mov_b32_e32 v80, 0
	v_mov_b32_e32 v81, v131
	v_mov_b32_e32 v82, v131
	v_mov_b32_e32 v83, v131
	v_mov_b32_e32 v84, 0
	v_mov_b32_e32 v85, v131
	v_mov_b32_e32 v86, v131
	v_mov_b32_e32 v87, v131
	v_mov_b32_e32 v74, v131
	v_mov_b32_e32 v75, v131
	v_mov_b32_e32 v62, v131
	v_mov_b32_e32 v63, v131
	v_mov_b32_e32 v36, 0
	v_mov_b32_e32 v37, v131
	v_mov_b32_e32 v38, v131
	v_mov_b32_e32 v39, v131
	v_mov_b32_e32 v54, 0
	v_mov_b32_e32 v55, v131
	v_mov_b32_e32 v56, v131
	v_mov_b32_e32 v57, v131
	v_mov_b32_e32 v32, 0
	v_mov_b32_e32 v33, v131
	v_mov_b32_e32 v34, v131
	v_mov_b32_e32 v35, v131
	v_mov_b32_e32 v64, 0
	v_mov_b32_e32 v65, v131
	v_mov_b32_e32 v66, v131
	v_mov_b32_e32 v67, v131
	v_mov_b32_e32 v40, 0
	v_mov_b32_e32 v41, v131
	v_mov_b32_e32 v42, v131
	v_mov_b32_e32 v43, v131
	v_mov_b32_e32 v48, 0
	v_mov_b32_e32 v49, v131
	v_mov_b32_e32 v50, v131
	v_mov_b32_e32 v51, v131
	v_mov_b32_e32 v68, 0
	v_mov_b32_e32 v69, v131
	v_mov_b32_e32 v70, v131
	v_mov_b32_e32 v71, v131
	v_mov_b32_e32 v72, 0
	v_mov_b32_e32 v73, v131
	v_readlane_b32 s100, v253, 0
	v_readlane_b32 s101, v253, 1
	s_load_dwordx2 s[100:101], s[100:101], 0x160
	v_lshrrev_b32_e32 v7, 6, v146
	s_nop 0
	v_readfirstlane_b32 s10, v7
	v_lshrrev_b32_e32 v5, 3, v146
	v_and_b32_e32 v6, 7, v146
	v_xor_b32_e32 v6, v5, v6
	v_and_b32_e32 v6, 7, v6
	v_lshlrev_b32_e32 v6, 4, v6
	v_lshl_or_b32 v4, v5, 11, v6
	v_add_u32_e32 v5, 0x10000, v4
	v_add_u32_e32 v6, 0x20000, v4
	v_add_u32_e32 v7, 0x30000, v4
	s_and_b32 s98, s45, 7
	s_lshl_b32 s98, s98, 3
	s_and_b32 s99, s69, 7
	s_or_b32 s98, s98, s99
	s_lshl_b32 s98, s98, 18
	s_add_u32 s98, s98, 0xdc40000
	s_lshr_b32 s99, s45, 3
	s_lshl_b32 s99, s99, 18
	s_add_u32 s99, s99, 0x8740000
	s_lshl_b32 s10, s10, 10
	s_waitcnt lgkmcnt(0)
	s_mov_b32 m0, s99
	s_add_u32 s98, s100, s98
	s_addc_u32 s99, s101, 0
	s_add_u32 s100, s100, m0
	s_addc_u32 s101, s101, 0
	s_add_u32 m0, s10, 0x0
	s_nop 0
	global_load_lds_dwordx4 v4, s[98:99]
	s_add_u32 m0, s10, 0x1000
	s_nop 0
	global_load_lds_dwordx4 v5, s[98:99]
	s_add_u32 m0, s10, 0x2000
	s_nop 0
	global_load_lds_dwordx4 v6, s[98:99]
	s_add_u32 m0, s10, 0x3000
	s_nop 0
	global_load_lds_dwordx4 v7, s[98:99]
	s_add_u32 m0, s10, 0x8000
	s_nop 0
	global_load_lds_dwordx4 v4, s[100:101]
	s_add_u32 m0, s10, 0x9000
	s_nop 0
	global_load_lds_dwordx4 v5, s[100:101]
	s_add_u32 m0, s10, 0xa000
	s_nop 0
	global_load_lds_dwordx4 v6, s[100:101]
	s_add_u32 m0, s10, 0xb000
	s_nop 0
	global_load_lds_dwordx4 v7, s[100:101]
	s_add_u32 s98, s98, 0x80
	s_addc_u32 s99, s99, 0
	s_add_u32 s100, s100, 0x80
	s_addc_u32 s101, s101, 0
	s_waitcnt vmcnt(0)
	s_waitcnt lgkmcnt(0)
	s_barrier
	s_bitcmp1_b32 s69, 8
	s_cbranch_scc1 .Lprio_h1166
	s_setprio 1
	s_branch .Lprio_j1166

.LBB0_1344:
	s_and_b32 s18, s97, 7
	s_or_b32 s18, s18, s0
	s_lshl_b32 s26, s18, 7
	s_lshl_b32 s24, s97, 4
	v_or_b32_e32 v0, s26, v149
	s_and_b32 s27, s24, 0x7fffff80
	v_lshl_or_b32 v96, v0, 11, v116
	v_or_b32_e32 v0, s27, v149
	s_waitcnt vmcnt(1)
	v_lshl_add_u64 v[100:101], s[10:11], 0, v[96:97]
	v_lshl_or_b32 v98, v0, 11, v116
	v_add_co_u32_e32 v0, vcc, 0x10000, v100
	v_mov_b32_e32 v99, v97
	s_nop 0
	v_addc_co_u32_e32 v1, vcc, 0, v101, vcc
	v_add_co_u32_e32 v2, vcc, 0x20000, v100
	v_lshl_add_u64 v[102:103], s[8:9], 0, v[98:99]
	s_nop 0
	v_addc_co_u32_e32 v3, vcc, 0, v101, vcc
	v_add_co_u32_e32 v6, vcc, 0x30000, v100
	s_nop 0
	v_addc_co_u32_e32 v7, vcc, 0, v101, vcc
	v_add_co_u32_e32 v12, vcc, s1, v102
	s_nop 0
	v_addc_co_u32_e32 v13, vcc, 0, v103, vcc
	v_add_co_u32_e32 v14, vcc, s4, v102
	s_nop 0
	v_addc_co_u32_e32 v15, vcc, 0, v103, vcc
	v_add_co_u32_e32 v48, vcc, s5, v102
	s_nop 0
	v_addc_co_u32_e32 v49, vcc, 0, v103, vcc
	s_movk_i32 s24, 0x100
	s_mov_b32 s28, s19
	v_mov_b32_e32 v8, 0
	v_mov_b32_e32 v9, v97
	v_mov_b32_e32 v10, v97
	v_mov_b32_e32 v11, v97
	v_mov_b32_e32 v4, 0
	v_mov_b32_e32 v5, v97
	v_mov_b32_e32 v6, v97
	v_mov_b32_e32 v7, v97
	v_mov_b32_e32 v12, 0
	v_mov_b32_e32 v13, v97
	v_mov_b32_e32 v14, v97
	v_mov_b32_e32 v15, v97
	v_mov_b32_e32 v0, 0
	v_mov_b32_e32 v1, v97
	v_lshl_add_u64 v[104:105], v[102:103], 0, s[12:13]
	v_lshl_add_u64 v[106:107], v[102:103], 0, s[14:15]
	v_lshl_add_u64 v[108:109], v[102:103], 0, s[16:17]
	v_lshl_add_u64 v[110:111], v[100:101], 0, s[12:13]
	v_lshl_add_u64 v[112:113], v[100:101], 0, s[14:15]
	v_lshl_add_u64 v[114:115], v[100:101], 0, s[16:17]
	s_barrier
	v_mov_b32_e32 v2, v97
	v_mov_b32_e32 v3, v97
	v_mov_b32_e32 v52, 0
	v_mov_b32_e32 v53, v97
	v_mov_b32_e32 v54, v97
	v_mov_b32_e32 v55, v97
	v_mov_b32_e32 v48, 0
	v_mov_b32_e32 v49, v97
	v_mov_b32_e32 v50, v97
	v_mov_b32_e32 v51, v97
	v_mov_b32_e32 v60, 0
	v_mov_b32_e32 v61, v97
	v_mov_b32_e32 v62, v97
	v_mov_b32_e32 v63, v97
	v_mov_b32_e32 v56, 0
	v_mov_b32_e32 v57, v97
	v_mov_b32_e32 v58, v97
	v_mov_b32_e32 v59, v97
	v_mov_b32_e32 v44, 0
	v_mov_b32_e32 v45, v97
	v_mov_b32_e32 v46, v97
	v_mov_b32_e32 v47, v97
	v_mov_b32_e32 v36, 0
	v_mov_b32_e32 v37, v97
	v_mov_b32_e32 v38, v97
	v_mov_b32_e32 v39, v97
	v_mov_b32_e32 v20, 0
	v_mov_b32_e32 v21, v97
	v_mov_b32_e32 v22, v97
	v_mov_b32_e32 v23, v97
	v_mov_b32_e32 v16, 0
	v_mov_b32_e32 v17, v97
	v_mov_b32_e32 v18, v97
	v_mov_b32_e32 v19, v97
	v_mov_b32_e32 v32, 0
	v_mov_b32_e32 v33, v97
	v_mov_b32_e32 v34, v97
	v_mov_b32_e32 v35, v97
	v_mov_b32_e32 v24, 0
	v_mov_b32_e32 v25, v97
	v_mov_b32_e32 v26, v97
	v_mov_b32_e32 v27, v97
	v_mov_b32_e32 v40, 0
	v_mov_b32_e32 v41, v97
	v_mov_b32_e32 v42, v97
	v_mov_b32_e32 v43, v97
	v_mov_b32_e32 v28, 0
	v_mov_b32_e32 v29, v97
	v_mov_b32_e32 v30, v97
	v_mov_b32_e32 v31, v97
	v_readlane_b32 s100, v253, 0
	v_readlane_b32 s101, v253, 1
	s_load_dwordx2 s[100:101], s[100:101], 0x160
	v_lshrrev_b32_e32 v71, 6, v146
	s_nop 0
	v_readfirstlane_b32 s30, v71
	v_lshrrev_b32_e32 v69, 3, v146
	v_and_b32_e32 v70, 7, v146
	v_xor_b32_e32 v70, v69, v70
	v_and_b32_e32 v70, 7, v70
	v_lshlrev_b32_e32 v70, 4, v70
	v_lshl_or_b32 v68, v69, 11, v70
	v_add_u32_e32 v69, 0x10000, v68
	v_add_u32_e32 v70, 0x20000, v68
	v_add_u32_e32 v71, 0x30000, v68
	s_and_b32 s98, s97, 7
	s_and_b32 s99, s69, 7
	s_lshl_b32 s99, s99, 3
	s_or_b32 s98, s98, s99
	s_lshl_b32 s98, s98, 18
	s_add_u32 s98, s98, 0x2000000
	s_lshr_b32 s99, s97, 3
	s_lshl_b32 s99, s99, 18
	s_add_u32 s99, s99, 0x9240000
	s_lshl_b32 s30, s30, 10
	s_waitcnt lgkmcnt(0)
	s_mov_b32 m0, s99
	s_add_u32 s98, s100, s98
	s_addc_u32 s99, s101, 0
	s_add_u32 s100, s100, m0
	s_addc_u32 s101, s101, 0
	s_add_u32 m0, s30, 0x0
	s_nop 0
	global_load_lds_dwordx4 v68, s[98:99]
	s_add_u32 m0, s30, 0x1000
	s_nop 0
	global_load_lds_dwordx4 v69, s[98:99]
	s_add_u32 m0, s30, 0x2000
	s_nop 0
	global_load_lds_dwordx4 v70, s[98:99]
	s_add_u32 m0, s30, 0x3000
	s_nop 0
	global_load_lds_dwordx4 v71, s[98:99]
	s_add_u32 m0, s30, 0x8000
	s_nop 0
	global_load_lds_dwordx4 v68, s[100:101]
	s_add_u32 m0, s30, 0x9000
	s_nop 0
	global_load_lds_dwordx4 v69, s[100:101]
	s_add_u32 m0, s30, 0xa000
	s_nop 0
	global_load_lds_dwordx4 v70, s[100:101]
	s_add_u32 m0, s30, 0xb000
	s_nop 0
	global_load_lds_dwordx4 v71, s[100:101]
	s_add_u32 s98, s98, 0x80
	s_addc_u32 s99, s99, 0
	s_add_u32 s100, s100, 0x80
	s_addc_u32 s101, s101, 0
	s_waitcnt vmcnt(0)
	s_waitcnt lgkmcnt(0)
	s_barrier
	s_bitcmp1_b32 s69, 8
	s_cbranch_scc1 .Lprio_h1345
	s_setprio 1
	s_branch .Lprio_j1345
